# K-loop: per-block setprio flips replaced by one static priority raise for waves 0-3 (strategy 7.4, other half)
# speedup vs baseline: 1.0157x; 1.0157x over previous
.Lfm2_done:
	s_and_b64 vcc, exec, s[80:81]
	s_cbranch_vccz .Lprio_skip
	s_setprio 1
